# first barrier: init-flag check and per-XCD arrival-count post moved from the end of P0 to the point between the weight conversion and the x conversion, so the discovery at the first barrier sees every
# speedup vs baseline: 1.0065x; 1.0065x over previous
; __device__ __forceinline__ unsigned pk2(float lo, float hi) { return f2bf(lo) | (f2bf(hi) << 16); }
; __device__ __forceinline__ void p0_prologue(const Params& p, LAS unsigned char* lds, int G) {
;     ...
;     for (int m0 = gw * 4; m0 < S; m0 += NGW * 4) {
;         f32x4 v[4][4];
; #pragma unroll
;         for (int rr = 0; rr < 4; ++rr) { const f32x4* xr = (const f32x4*)(p.x + (size_t)(m0 + rr) * DM) + lane;
; #pragma unroll
;             for (int j = 0; j < 4; ++j) v[rr][j] = __builtin_nontemporal_load(xr + 64 * j); }
; #pragma unroll
;         for (int rr = 0; rr < 4; ++rr) {
;             float s = 0.f;
; #pragma unroll
;             for (int j = 0; j < 4; ++j) s += (v[rr][j][0] * v[rr][j][0] + v[rr][j][1] * v[rr][j][1]) + (v[rr][j][2] * v[rr][j][2] + v[rr][j][3] * v[rr][j][3]);
;             s = wave_sum(s);
;             u32x2* o8 = (u32x2*)(XB + (size_t)(m0 + rr) * DM) + lane;
; #pragma unroll
;             for (int j = 0; j < 4; ++j) { u32x2 w; w.x = pk2(v[rr][j][0], v[rr][j][1]); w.y = pk2(v[rr][j][2], v[rr][j][3]); o8[64 * j] = w; }
;             if (lane < 16) SS0[(size_t)(m0 + rr) * 16 + lane] = lane == 0 ? s : 0.f;
; __global__ void __launch_bounds__(512, 2) fwd_megakernel(Params p) {
;     ...
;         unsigned* flag = barw + 16384 - 64;
;         constexpr unsigned MAGIC = 0x600DF1A6u;
;         if (blockIdx.x == 0) {
;             for (int i = threadIdx.x; i < 16384 - 64; i += 512) barw[i] = 0u;
;             __threadfence(); __syncthreads();
;             if (threadIdx.x == 0) { asm volatile("s_waitcnt vmcnt(0)" ::: "memory"); __hip_atomic_store(flag, MAGIC, __ATOMIC_RELEASE, __HIP_MEMORY_SCOPE_AGENT); }
;         } else if (threadIdx.x == 0) {
;             unsigned sp = 0; while (__hip_atomic_load(flag, __ATOMIC_RELAXED, __HIP_MEMORY_SCOPE_AGENT) != MAGIC) { __builtin_amdgcn_s_sleep(1); if (++sp > (1u << 22)) break; }
;             __builtin_amdgcn_fence(__ATOMIC_ACQUIRE, "agent");
;         }
.LBB0_51:
	v_cmp_eq_u32_e32 vcc, 0, v152
	s_and_saveexec_b64 s[4:5], vcc
	s_cbranch_execz .Learly_done
	s_cmp_lg_u32 s86, 0
	s_cbranch_scc0 .Learly_post
	v_mov_b32_e32 v0, 0
	s_mov_b32 s3, 0x400001
.Learly_spin:
	global_load_dword v1, v0, s[26:27] sc1
	s_waitcnt vmcnt(0)
	v_cmp_eq_u32_e32 vcc, 0x600df1a6, v1
	s_cbranch_vccnz .Learly_post
	s_sleep 1
	s_add_i32 s3, s3, -1
	s_cmp_eq_u32 s3, 0
	s_cbranch_scc0 .Learly_spin
.Learly_post:
	v_readlane_b32 s3, v255, 1
	s_nop 3
	s_lshl_b32 s3, s3, 8
	v_mov_b32_e32 v0, s3
	v_mov_b32_e32 v1, 1
	global_atomic_add v0, v1, s[96:97] offset:1024
.Learly_done:
	s_or_b64 exec, exec, s[4:5]
	s_cmpk_gt_i32 s2, 0xfff
	v_cmp_gt_u32_e64 s[0:1], 16, v153
	v_cmp_eq_u32_e64 s[4:5], 0, v153
	v_lshlrev_b32_e32 v174, 4, v153
	s_cbranch_scc1 .LBB0_62
	v_mbcnt_lo_u32_b32 v0, -1, 0
	v_mbcnt_hi_u32_b32 v0, -1, v0
	v_and_b32_e32 v1, 64, v0
	v_add_u32_e32 v1, 64, v1
	v_xor_b32_e32 v2, 1, v0
	v_cmp_lt_i32_e32 vcc, v2, v1
	s_lshl_b32 s10, s2, 2
	s_ashr_i32 s11, s10, 31
	v_cndmask_b32_e32 v2, v0, v2, vcc
	v_lshlrev_b32_e32 v60, 2, v2
	v_xor_b32_e32 v2, 2, v0
	v_cmp_lt_i32_e32 vcc, v2, v1
	s_lshl_b32 s12, s74, 5
	s_lshl_b64 s[2:3], s[10:11], 12
	v_cndmask_b32_e32 v2, v0, v2, vcc
	v_lshlrev_b32_e32 v61, 2, v2
	v_xor_b32_e32 v2, 4, v0
	v_cmp_lt_i32_e32 vcc, v2, v1
	s_add_u32 s2, s8, s2
	v_mov_b32_e32 v175, 0
	v_cndmask_b32_e32 v2, v0, v2, vcc
	v_lshlrev_b32_e32 v62, 2, v2
	v_xor_b32_e32 v2, 8, v0
	v_cmp_lt_i32_e32 vcc, v2, v1
	s_addc_u32 s3, s9, s3
	s_ashr_i32 s13, s12, 31
	v_cndmask_b32_e32 v2, v0, v2, vcc
	v_lshlrev_b32_e32 v63, 2, v2
	v_xor_b32_e32 v2, 16, v0
	v_cmp_lt_i32_e32 vcc, v2, v1
	s_lshl_b64 s[8:9], s[12:13], 12
	s_lshl_b64 s[14:15], s[12:13], 11
	v_cndmask_b32_e32 v2, v0, v2, vcc
	v_lshlrev_b32_e32 v64, 2, v2
	v_xor_b32_e32 v2, 32, v0
	v_cmp_lt_i32_e32 vcc, v2, v1
	s_lshl_b64 s[28:29], s[12:13], 6
	s_mov_b32 s13, 0xa801000
	v_cndmask_b32_e32 v0, v0, v2, vcc
	v_lshlrev_b32_e32 v65, 2, v0
	v_lshl_add_u64 v[0:1], s[2:3], 0, v[174:175]
	s_mov_b64 s[2:3], 0x3c00
	v_lshl_add_u64 v[48:49], v[0:1], 0, s[2:3]
	s_lshl_b64 s[2:3], s[10:11], 11
	v_lshl_or_b32 v50, v153, 3, s2
	v_mov_b32_e32 v51, s3
	s_lshl_b64 s[2:3], s[10:11], 6
	v_lshl_or_b32 v52, v153, 2, s2
	v_mov_b32_e32 v53, s3
	s_movk_i32 s2, 0x7fff
	s_mov_b32 s3, 0xffff0000
	s_mov_b32 s11, 0xa800000
	s_branch .LBB0_54

; __device__ __forceinline__ unsigned pk2(float lo, float hi) { return f2bf(lo) | (f2bf(hi) << 16); }
; __device__ __forceinline__ void p0_prologue(const Params& p, LAS unsigned char* lds, int G) {
;     ...
;         for (int rr = 0; rr < 4; ++rr) {
;             float s = 0.f;
; #pragma unroll
;             for (int j = 0; j < 4; ++j) s += (v[rr][j][0] * v[rr][j][0] + v[rr][j][1] * v[rr][j][1]) + (v[rr][j][2] * v[rr][j][2] + v[rr][j][3] * v[rr][j][3]);
;             s = wave_sum(s);
;             u32x2* o8 = (u32x2*)(XB + (size_t)(m0 + rr) * DM) + lane;
; #pragma unroll
;             for (int j = 0; j < 4; ++j) { u32x2 w; w.x = pk2(v[rr][j][0], v[rr][j][1]); w.y = pk2(v[rr][j][2], v[rr][j][3]); o8[64 * j] = w; }
;             if (lane < 16) SS0[(size_t)(m0 + rr) * 16 + lane] = lane == 0 ? s : 0.f;
; __device__ __forceinline__ void xcd_barrier(const XcdBarrier& b) {
;     asm volatile("s_waitcnt vmcnt(0)" ::: "memory");
;     __syncthreads();
.LBB0_60:
	s_or_b64 exec, exec, s[6:7]
	v_mul_f32_e32 v16, v13, v13
	v_mul_f32_e32 v17, v15, v15
	v_fmac_f32_e32 v16, v12, v12
	v_fmac_f32_e32 v17, v14, v14
	v_add_f32_e32 v16, v16, v17
	v_mul_f32_e32 v17, v9, v9
	v_mul_f32_e32 v18, v11, v11
	v_fmac_f32_e32 v17, v8, v8
	v_fmac_f32_e32 v18, v10, v10
	v_add_f32_e32 v17, v17, v18
	v_add_f32_e32 v16, v16, v17
	v_mul_f32_e32 v17, v5, v5
	v_mul_f32_e32 v18, v7, v7
	v_fmac_f32_e32 v17, v4, v4
	v_fmac_f32_e32 v18, v6, v6
	v_add_f32_e32 v17, v17, v18
	v_add_f32_e32 v16, v16, v17
	v_mul_f32_e32 v17, v1, v1
	v_mul_f32_e32 v18, v3, v3
	v_fmac_f32_e32 v17, v0, v0
	v_fmac_f32_e32 v18, v2, v2
	v_add_f32_e32 v17, v17, v18
	v_add_f32_e32 v16, v16, v17
	ds_bpermute_b32 v17, v60, v16
	v_bfe_u32 v18, v12, 16, 1
	v_add3_u32 v12, v12, v18, s2
	v_lshrrev_b32_e32 v18, 16, v12
	s_waitcnt lgkmcnt(0)
	v_add_f32_e32 v16, v16, v17
	ds_bpermute_b32 v17, v61, v16
	s_waitcnt lgkmcnt(0)
	v_add_f32_e32 v16, v16, v17
	ds_bpermute_b32 v17, v62, v16
	s_waitcnt lgkmcnt(0)
	v_add_f32_e32 v16, v16, v17
	ds_bpermute_b32 v17, v63, v16
	s_waitcnt lgkmcnt(0)
	v_add_f32_e32 v16, v16, v17
	ds_bpermute_b32 v17, v64, v16
	s_waitcnt lgkmcnt(0)
	v_add_f32_e32 v12, v16, v17
	v_bfe_u32 v17, v13, 16, 1
	v_add3_u32 v13, v13, v17, s2
	v_and_or_b32 v18, v13, s3, v18
	v_bfe_u32 v13, v14, 16, 1
	v_add3_u32 v13, v14, v13, s2
	v_bfe_u32 v14, v15, 16, 1
	v_lshrrev_b32_e32 v13, 16, v13
	v_add3_u32 v14, v15, v14, s2
	v_and_or_b32 v19, v14, s3, v13
	v_bfe_u32 v13, v8, 16, 1
	v_add3_u32 v8, v8, v13, s2
	v_bfe_u32 v13, v9, 16, 1
	v_lshrrev_b32_e32 v8, 16, v8
	v_add3_u32 v9, v9, v13, s2
	v_and_or_b32 v8, v9, s3, v8
	v_bfe_u32 v9, v10, 16, 1
	v_add3_u32 v9, v10, v9, s2
	v_bfe_u32 v10, v11, 16, 1
	v_lshrrev_b32_e32 v9, 16, v9
	v_add3_u32 v10, v11, v10, s2
	v_and_or_b32 v9, v10, s3, v9
	global_store_dwordx2 v[28:29], v[8:9], off offset:2560
	v_bfe_u32 v8, v4, 16, 1
	v_add3_u32 v4, v4, v8, s2
	v_bfe_u32 v8, v5, 16, 1
	v_lshrrev_b32_e32 v4, 16, v4
	v_add3_u32 v5, v5, v8, s2
	v_and_or_b32 v4, v5, s3, v4
	v_bfe_u32 v5, v6, 16, 1
	v_add3_u32 v5, v6, v5, s2
	v_bfe_u32 v6, v7, 16, 1
	v_lshrrev_b32_e32 v5, 16, v5
	v_add3_u32 v6, v7, v6, s2
	v_and_or_b32 v5, v6, s3, v5
	global_store_dwordx2 v[28:29], v[4:5], off offset:3072
	v_bfe_u32 v4, v0, 16, 1
	v_add3_u32 v0, v0, v4, s2
	v_bfe_u32 v4, v1, 16, 1
	ds_bpermute_b32 v16, v65, v12
	v_lshrrev_b32_e32 v0, 16, v0
	v_add3_u32 v1, v1, v4, s2
	v_and_or_b32 v0, v1, s3, v0
	v_bfe_u32 v1, v2, 16, 1
	v_add3_u32 v1, v2, v1, s2
	v_bfe_u32 v2, v3, 16, 1
	v_lshrrev_b32_e32 v1, 16, v1
	v_add3_u32 v2, v3, v2, s2
	v_and_or_b32 v1, v2, s3, v1
	global_store_dwordx2 v[28:29], v[18:19], off offset:2048
	global_store_dwordx2 v[28:29], v[0:1], off offset:3584
	s_and_saveexec_b64 s[6:7], s[0:1]
	s_cbranch_execz .LBB0_53
	s_waitcnt lgkmcnt(0)
	v_add_f32_e32 v0, v12, v16
	v_cndmask_b32_e64 v0, 0, v0, s[4:5]
	global_store_dword v[54:55], v0, off offset:192
	s_branch .LBB0_53
.LBB0_62:
	s_waitcnt vmcnt(0)
	s_waitcnt lgkmcnt(0)
	s_barrier
	v_readfirstlane_b32 s2, v152
	s_cmp_lg_u32 s2, 64
	s_cbranch_scc1 .Leinv_skip_0
	buffer_inv sc1
	s_waitcnt vmcnt(0)
